# nt4 + gdn-prep units visited chunk-major (u = 36*(vcu&31)+(vcu>>5)+8i) so record production order matches scan consumption / evictions spread over all chains
# speedup vs baseline: 1.0105x; 1.0105x over previous
; #define LAS __attribute__((address_space(3)))
; #define LDS_BARRIER() asm volatile("s_waitcnt lgkmcnt(0)\n\ts_barrier" ::: "memory")
; __device__ __forceinline__ void gdn_prep_phase(const Frame& F0, const Args& a0, int l) {
;     const Frame F = relaunder(F0); const Args a = relaunder_args(a0);
;     const bf16* Z = (const bf16*)(a.ws + WS_Z); const float* AB = (const float*)(a.ws + WS_AB);
;     const float* convw = a.in[I_CONVW] + (size_t)l * 5 * 3072; const float* alog = a.in[I_ALOG] + l * 16; const float* dtb = a.in[I_DTB] + l * 16;
;     unsigned char* RECB = a.ws + WS_GREC; float* UB = (float*)(a.ws + WS_GU); float* GLB = (float*)(a.ws + WS_GL);
;     LAS unsigned char* lds = F.lds + RING_OFF;
;     const int tid = F.tid, lane = F.lane, wave = F.wave;
;     LAS float* gcs = (LAS float*)(lds + GD_GATES); LAS float* bts = gcs + 128; LAS float* egs = gcs + 256; LAS float* ekd = gcs + 384;
;     v2u zr[20]; f32x4 cw[5]; float pab0 = 0.f, pab1 = 0.f;
;     ...
;     if (F.vcu < NB * 8 * 36) GD_PREFETCH(F.vcu);
;     for (int u = F.vcu; u < NB * 8 * 36; u += F.G) {
;         const int c = u % 36, h = (u / 36) & 7, b = u / 288;
;         LDS_BARRIER();
.LBB0_372:
	s_cmp_le_i32 s64, s18
	s_cselect_b64 s[0:1], -1, 0
	s_and_b64 s[30:31], s[0:1], s[2:3]
	s_andn2_b64 vcc, exec, s[30:31]
	s_cbranch_vccnz .LBB0_513
	s_and_b32 s27, s93, 31
	s_mul_i32 s27, s27, 36
	s_lshr_b32 s98, s93, 5
	s_add_i32 s27, s27, s98
	s_cmpk_lt_i32 s93, 0x80
	s_cselect_b32 s98, 40, 32
	s_add_i32 s98, s98, s27
	s_mov_b32 s0, s94
	s_mov_b32 s14, s95
	s_mov_b32 s22, 8
	v_readlane_b32 s48, v221, 0
	s_waitcnt vmcnt(0)
	v_mbcnt_lo_u32_b32 v22, -1, 0
	v_mbcnt_hi_u32_b32 v22, -1, v22
	v_readlane_b32 s49, v221, 1
	s_mov_b64 s[0:1], s[48:49]
	v_readlane_b32 s50, v221, 2
	v_readlane_b32 s51, v221, 3
	s_mov_b64 s[0:1], s[50:51]
	v_readlane_b32 s52, v221, 4
	v_readlane_b32 s53, v221, 5
	s_mov_b64 s[0:1], s[52:53]
	v_readlane_b32 s54, v221, 6
	v_readlane_b32 s55, v221, 7
	s_mov_b64 s[0:1], s[54:55]
	v_readlane_b32 s56, v221, 8
	v_readlane_b32 s57, v221, 9
	s_mov_b64 s[0:1], s[56:57]
	v_readlane_b32 s58, v221, 10
	v_readlane_b32 s59, v221, 11
	s_mov_b64 s[0:1], s[58:59]
	v_readlane_b32 s60, v221, 12
	v_readlane_b32 s61, v221, 13
	s_mov_b64 s[0:1], s[60:61]
	v_readlane_b32 s62, v221, 14
	v_readlane_b32 s63, v221, 15
	s_mov_b64 s[0:1], s[62:63]
	v_readlane_b32 s64, v221, 16
	v_readlane_b32 s65, v221, 17
	v_readlane_b32 s66, v221, 18
	v_readlane_b32 s67, v221, 19
	v_readlane_b32 s68, v221, 20
	v_readlane_b32 s69, v221, 21
	v_readlane_b32 s70, v221, 22
	v_readlane_b32 s71, v221, 23
	s_mov_b64 s[2:3], s[64:65]
	s_mov_b64 s[6:7], s[66:67]
	s_mov_b64 s[8:9], s[68:69]
	s_mov_b64 s[0:1], s[70:71]
	v_readlane_b32 s72, v221, 24
	v_readlane_b32 s73, v221, 25
	s_mov_b64 s[0:1], s[72:73]
	v_readlane_b32 s74, v221, 26
	v_readlane_b32 s75, v221, 27
	s_mov_b64 s[0:1], s[74:75]
	v_readlane_b32 s76, v221, 28
	v_readlane_b32 s77, v221, 29
	s_mov_b64 s[0:1], s[76:77]
	v_readlane_b32 s78, v221, 30
	v_readlane_b32 s79, v221, 31
	s_mov_b64 s[0:1], s[78:79]
	s_mov_b64 s[0:1], s[40:41]
	s_mov_b64 s[0:1], s[42:43]
	s_mov_b64 s[0:1], s[44:45]
	s_mov_b64 s[10:11], s[46:47]
	s_add_u32 s76, s10, 0x1ec00000
	s_addc_u32 s77, s11, 0
	s_add_u32 s0, s10, 0x25400000
	s_mul_i32 s5, s24, 0xf000
	s_addc_u32 s1, s11, 0
	s_mul_hi_u32 s4, s24, 0xf000
	s_add_u32 s62, s2, s5
	s_addc_u32 s63, s3, s4
	s_cmp_lt_i32 s27, s98
	v_mov_b32_e32 v129, 0
	s_cselect_b64 s[12:13], -1, 0
	s_cmp_ge_i32 s27, s98
	v_mov_b32_e32 v130, 0
	s_cbranch_scc1 .LBB0_395
	s_cmp_lt_i32 s14, 4
	v_mbcnt_lo_u32_b32 v23, -1, 0
	v_mbcnt_hi_u32_b32 v23, -1, v23
	s_cselect_b64 s[2:3], -1, 0
	s_cmp_gt_i32 s14, 3
	v_ashrrev_i32_e32 v0, 5, v23
	s_mov_b64 s[4:5], -1
	s_cbranch_scc0 .LBB0_376
	s_lshl_b32 s4, s14, 1
	s_add_i32 s4, s4, -8
	v_add_lshl_u32 v24, s4, v0, 3
	s_mov_b64 s[4:5], 0

; #define LDS_BARRIER() asm volatile("s_waitcnt lgkmcnt(0)\n\ts_barrier" ::: "memory")
; __device__ __forceinline__ void gdn_prep_phase(const Frame& F0, const Args& a0, int l) {
;     ...
;     if (F.vcu < NB * 8 * 36) GD_PREFETCH(F.vcu);
;     for (int u = F.vcu; u < NB * 8 * 36; u += F.G) {
;         const int c = u % 36, h = (u / 36) & 7, b = u / 288;
;         LDS_BARRIER();
.LBB0_420:
	s_add_i32 s27, s27, s22
	s_cmp_lt_i32 s27, s98
	s_waitcnt lgkmcnt(0)
	s_barrier
	s_cselect_b64 s[12:13], -1, 0
	s_cmp_ge_i32 s27, s98
	s_cselect_b64 s[68:69], -1, 0
	v_cndmask_b32_e64 v20, 0, 1, s[2:3]
	s_and_b64 vcc, exec, s[68:69]
	v_cmp_ne_u32_e64 s[8:9], 1, v20
	s_cbranch_vccnz .LBB0_438
	s_mul_hi_i32 s11, s27, 0x38e38e39
	s_ashr_i32 s10, s11, 3
	s_lshr_b32 s14, s11, 31
	s_add_i32 s53, s10, s14
	s_mul_i32 s10, s53, 0xffffffdc
	v_mbcnt_lo_u32_b32 v22, -1, 0
	v_mbcnt_hi_u32_b32 v22, -1, v22
	s_add_i32 s15, s27, s10
	v_ashrrev_i32_e32 v0, 5, v22
	s_and_b32 s10, s53, 7
	s_lshr_b32 s11, s11, 6
	v_add_lshl_u32 v23, v0, s73, 3
	v_lshlrev_b32_e32 v0, 10, v0
	v_lshlrev_b32_e32 v1, 2, v22
	s_add_i32 s54, s11, s14
	s_mul_i32 s14, s53, 0xfffff700
	s_add_i32 s11, s49, s45
	s_lshl_b32 s56, s10, 7
	v_cndmask_b32_e64 v0, v188, v0, s[2:3]
	v_and_b32_e32 v1, 0x7c, v1
	s_add_i32 s55, s11, s14
	v_or3_b32 v20, v0, s56, v1
	s_add_i32 s57, s55, 0xffffff00
	v_ashrrev_i32_e32 v21, 31, v20
	s_cmp_lt_i32 s15, 4
	v_lshl_add_u64 v[16:17], v[20:21], 2, s[62:63]
	s_movk_i32 s15, 0x3000
	v_add_co_u32_e32 v4, vcc, s15, v16
	s_movk_i32 s15, 0x6000
	s_nop 0
	v_addc_co_u32_e32 v5, vcc, 0, v17, vcc
	v_add_co_u32_e32 v8, vcc, s15, v16
	s_mov_b32 s15, 0x9000
	s_nop 0
	v_addc_co_u32_e32 v9, vcc, 0, v17, vcc
	v_add_co_u32_e32 v12, vcc, s15, v16
	s_mov_b32 s15, 0xc000
	s_nop 0
	v_addc_co_u32_e32 v13, vcc, 0, v17, vcc
	v_mov_b32_e32 v24, s25
	global_load_dwordx4 v[0:3], v[16:17], off
	s_nop 0
	global_load_dwordx4 v[4:7], v[4:5], off
	v_add_co_u32_e32 v16, vcc, s15, v16
	s_mul_i32 s15, s54, 0x900
	s_cselect_b32 s54, s55, s57
	v_cndmask_b32_e64 v23, v23, v24, s[2:3]
	s_movk_i32 s14, 0x7ff
	v_add_u32_e32 v23, s54, v23
	s_cselect_b32 s14, 0xff, s14
	v_addc_co_u32_e32 v17, vcc, 0, v17, vcc
	v_add_u32_e32 v24, -2, v23
	v_min_i32_e32 v24, s14, v24
	v_cmp_lt_i32_e32 vcc, 1, v23
	v_or_b32_e32 v34, 1, v23
	v_add_u32_e32 v30, -1, v23
	v_cndmask_b32_e32 v24, 0, v24, vcc
	v_min_i32_e32 v30, s14, v30
	v_cmp_lt_i32_e32 vcc, 1, v34
	v_min_i32_e32 v32, s14, v23
	v_min_i32_e32 v34, s14, v34
	v_cndmask_b32_e32 v30, 0, v30, vcc
	v_cmp_gt_i32_e32 vcc, 0, v23
	v_add_u32_e32 v24, s15, v24
	v_subrev_u32_e32 v24, s54, v24
	v_cndmask_b32_e64 v32, v32, 0, vcc
	v_cndmask_b32_e64 v34, v34, 0, vcc
	s_mulk_i32 s53, 0x900
	v_add_u32_e32 v30, s15, v30
	v_add_u32_e32 v32, s15, v32
	v_add_u32_e32 v34, s15, v34
	v_subrev_u32_e32 v24, s53, v24
	v_subrev_u32_e32 v30, s54, v30
	v_subrev_u32_e32 v32, s54, v32
	v_subrev_u32_e32 v34, s54, v34
	v_add_u32_e32 v26, s11, v24
	v_mov_b64_e32 v[24:25], s[76:77]
	v_subrev_u32_e32 v30, s53, v30
	v_subrev_u32_e32 v32, s53, v32
	v_subrev_u32_e32 v34, s53, v34
	v_mad_i64_i32 v[26:27], s[56:57], v26, s87, v[24:25]
	v_lshlrev_b64 v[28:29], 1, v[20:21]
	v_add_u32_e32 v30, s11, v30
	v_add_u32_e32 v32, s11, v32
	v_add_u32_e32 v34, s11, v34
	v_lshl_add_u64 v[26:27], v[26:27], 0, v[28:29]
	v_mad_i64_i32 v[30:31], s[56:57], v30, s87, v[24:25]
	v_mad_i64_i32 v[32:33], s[56:57], v32, s87, v[24:25]
	v_mad_i64_i32 v[34:35], s[56:57], v34, s87, v[24:25]
	global_load_dwordx4 v[8:11], v[8:9], off
	s_nop 0
	global_load_dwordx4 v[12:15], v[12:13], off
	v_lshl_add_u64 v[30:31], v[30:31], 0, v[28:29]
	global_load_dwordx4 v[16:19], v[16:17], off
	v_lshl_add_u64 v[32:33], v[32:33], 0, v[28:29]
	v_lshl_add_u64 v[34:35], v[34:35], 0, v[28:29]
	global_load_dwordx2 v[64:65], v[26:27], off offset:3072 nt
	global_load_dwordx2 v[66:67], v[30:31], off offset:3072 nt
	global_load_dwordx2 v[72:73], v[32:33], off offset:3072 nt
	global_load_dwordx2 v[74:75], v[34:35], off offset:3072 nt
	v_or_b32_e32 v26, 2, v23
	v_min_i32_e32 v26, s14, v26
	v_or_b32_e32 v30, 3, v23
	v_or_b32_e32 v32, 4, v23
	v_or_b32_e32 v34, 5, v23
	v_cndmask_b32_e64 v26, v26, 0, vcc
	v_min_i32_e32 v30, s14, v30
	v_min_i32_e32 v32, s14, v32
	v_min_i32_e32 v34, s14, v34
	v_add_u32_e32 v26, s15, v26
	v_cndmask_b32_e64 v30, v30, 0, vcc
	v_cndmask_b32_e64 v32, v32, 0, vcc
	v_cndmask_b32_e64 v34, v34, 0, vcc
	v_subrev_u32_e32 v26, s54, v26
	v_add_u32_e32 v30, s15, v30
	v_add_u32_e32 v32, s15, v32
	v_add_u32_e32 v34, s15, v34
	v_subrev_u32_e32 v26, s53, v26
	v_subrev_u32_e32 v30, s54, v30
	v_subrev_u32_e32 v32, s54, v32
	v_subrev_u32_e32 v34, s54, v34
	v_add_u32_e32 v26, s11, v26
	v_subrev_u32_e32 v30, s53, v30
	v_subrev_u32_e32 v32, s53, v32
	v_subrev_u32_e32 v34, s53, v34
	v_mad_i64_i32 v[26:27], s[56:57], v26, s87, v[24:25]
	v_add_u32_e32 v30, s11, v30
	v_add_u32_e32 v32, s11, v32
	v_add_u32_e32 v34, s11, v34
	v_lshl_add_u64 v[26:27], v[26:27], 0, v[28:29]
	v_mad_i64_i32 v[30:31], s[56:57], v30, s87, v[24:25]
	v_mad_i64_i32 v[32:33], s[56:57], v32, s87, v[24:25]
	v_mad_i64_i32 v[34:35], s[56:57], v34, s87, v[24:25]
	v_lshl_add_u64 v[30:31], v[30:31], 0, v[28:29]
	v_lshl_add_u64 v[32:33], v[32:33], 0, v[28:29]
	v_lshl_add_u64 v[34:35], v[34:35], 0, v[28:29]
	global_load_dwordx2 v[84:85], v[26:27], off offset:3072 nt
	global_load_dwordx2 v[86:87], v[30:31], off offset:3072 nt
	global_load_dwordx2 v[88:89], v[32:33], off offset:3072 nt
	global_load_dwordx2 v[90:91], v[34:35], off offset:3072 nt
	v_or_b32_e32 v26, 6, v23
	v_min_i32_e32 v26, s14, v26
	v_cmp_lt_i32_e32 vcc, -7, v23
	v_or_b32_e32 v30, 7, v23
	v_min_i32_e32 v30, s14, v30
	v_cndmask_b32_e32 v26, 0, v26, vcc
	v_cmp_lt_i32_e32 vcc, -8, v23
	v_add_u32_e32 v32, 8, v23
	v_min_i32_e32 v32, s14, v32
	v_cndmask_b32_e32 v30, 0, v30, vcc
	v_cmp_lt_i32_e32 vcc, -9, v23
	v_add_u32_e32 v34, 9, v23
	v_min_i32_e32 v34, s14, v34
	v_cndmask_b32_e32 v32, 0, v32, vcc
	v_cmp_lt_i32_e32 vcc, -10, v23
	v_add_u32_e32 v26, s15, v26
	v_subrev_u32_e32 v26, s54, v26
	v_cndmask_b32_e32 v34, 0, v34, vcc
	v_add_u32_e32 v30, s15, v30
	v_add_u32_e32 v32, s15, v32
	v_add_u32_e32 v34, s15, v34
	v_subrev_u32_e32 v26, s53, v26
	v_subrev_u32_e32 v30, s54, v30
	v_subrev_u32_e32 v32, s54, v32
	v_subrev_u32_e32 v34, s54, v34
	v_add_u32_e32 v26, s11, v26
	v_subrev_u32_e32 v30, s53, v30
	v_subrev_u32_e32 v32, s53, v32
	v_subrev_u32_e32 v34, s53, v34
	v_mad_i64_i32 v[26:27], s[56:57], v26, s87, v[24:25]
	v_add_u32_e32 v30, s11, v30
	v_add_u32_e32 v32, s11, v32
	v_add_u32_e32 v34, s11, v34
	v_lshl_add_u64 v[26:27], v[26:27], 0, v[28:29]
	v_mad_i64_i32 v[30:31], s[56:57], v30, s87, v[24:25]
	v_mad_i64_i32 v[32:33], s[56:57], v32, s87, v[24:25]
	v_mad_i64_i32 v[24:25], s[56:57], v34, s87, v[24:25]
	v_lshl_add_u64 v[30:31], v[30:31], 0, v[28:29]
	v_lshl_add_u64 v[32:33], v[32:33], 0, v[28:29]
	v_lshl_add_u64 v[24:25], v[24:25], 0, v[28:29]
	global_load_dwordx2 v[96:97], v[26:27], off offset:3072 nt
	global_load_dwordx2 v[98:99], v[30:31], off offset:3072 nt
	global_load_dwordx2 v[100:101], v[32:33], off offset:3072 nt
	global_load_dwordx2 v[102:103], v[24:25], off offset:3072 nt
	s_and_b64 vcc, exec, s[8:9]
	s_cbranch_vccnz .LBB0_429
	v_add_u32_e32 v24, 10, v23
	v_min_i32_e32 v24, s14, v24
	v_cmp_lt_i32_e32 vcc, -11, v23
	s_nop 1
	v_cndmask_b32_e32 v24, 0, v24, vcc
	v_add_u32_e32 v24, s15, v24
	v_subrev_u32_e32 v24, s54, v24
	v_subrev_u32_e32 v24, s53, v24
	v_add_u32_e32 v26, s11, v24
	v_mov_b64_e32 v[24:25], s[76:77]
	v_mad_i64_i32 v[24:25], s[56:57], v26, s87, v[24:25]
	v_lshl_add_u64 v[24:25], v[20:21], 1, v[24:25]
	global_load_dwordx2 v[68:69], v[24:25], off offset:3072 nt
	s_and_b64 vcc, exec, s[8:9]
	s_cbranch_vccz .LBB0_430
